# e14: wo2_convert tile loads issued 32-deep before the first LDS write (was 4-deep with full waits), on top of e11 + scan DMA nt
# speedup vs baseline: 1.0175x; 1.0175x over previous
.Le14_rd:
	s_waitcnt lgkmcnt(0)
	s_sub_i32 s4, 0, s1
	ds_read2_b32 v[6:7], v41 offset1:33
	s_add_i32 s4, s4, s9
	s_waitcnt lgkmcnt(0)
	v_cvt_pk_bf16_f32 v48, v6, v7
	ds_read2_b32 v[6:7], v41 offset0:66 offset1:99
	v_add_u32_e32 v54, s4, v40
	s_waitcnt lgkmcnt(0)
	v_cvt_pk_bf16_f32 v49, v6, v7
	ds_read2_b32 v[6:7], v41 offset0:132 offset1:165
	s_ashr_i32 s1, s0, 31
	v_ashrrev_i32_e32 v55, 31, v54
	s_waitcnt lgkmcnt(0)
	v_cvt_pk_bf16_f32 v50, v6, v7
	ds_read2_b32 v[6:7], v41 offset0:198 offset1:231
	v_lshl_add_u64 v[52:53], s[0:1], 1, v[4:5]
	v_lshlrev_b64 v[56:57], 13, v[54:55]
	s_waitcnt lgkmcnt(0)
	v_cvt_pk_bf16_f32 v51, v6, v7
	ds_read2_b32 v[6:7], v41 offset0:8 offset1:41
	v_lshl_add_u64 v[56:57], v[52:53], 0, v[56:57]
	global_store_dwordx4 v[56:57], v[48:51], off
	v_add_u32_e32 v56, 8, v54
	v_ashrrev_i32_e32 v57, 31, v56
	s_waitcnt lgkmcnt(0)
	v_cvt_pk_bf16_f32 v48, v6, v7
	ds_read2_b32 v[6:7], v41 offset0:74 offset1:107
	s_waitcnt lgkmcnt(0)
	v_cvt_pk_bf16_f32 v49, v6, v7
	ds_read2_b32 v[6:7], v41 offset0:140 offset1:173
	s_waitcnt lgkmcnt(0)
	v_cvt_pk_bf16_f32 v50, v6, v7
	ds_read2_b32 v[6:7], v41 offset0:206 offset1:239
	v_lshlrev_b64 v[56:57], 13, v[56:57]
	s_waitcnt lgkmcnt(0)
	v_cvt_pk_bf16_f32 v51, v6, v7
	ds_read2_b32 v[6:7], v41 offset0:16 offset1:49
	v_lshl_add_u64 v[56:57], v[52:53], 0, v[56:57]
	global_store_dwordx4 v[56:57], v[48:51], off
	v_add_u32_e32 v56, 16, v54
	v_ashrrev_i32_e32 v57, 31, v56
	s_waitcnt lgkmcnt(0)
	v_cvt_pk_bf16_f32 v48, v6, v7
	ds_read2_b32 v[6:7], v41 offset0:82 offset1:115
	s_waitcnt lgkmcnt(0)
	v_cvt_pk_bf16_f32 v49, v6, v7
	ds_read2_b32 v[6:7], v41 offset0:148 offset1:181
	s_waitcnt lgkmcnt(0)
	v_cvt_pk_bf16_f32 v50, v6, v7
	ds_read2_b32 v[6:7], v41 offset0:214 offset1:247
	v_lshlrev_b64 v[56:57], 13, v[56:57]
	v_add_u32_e32 v54, 24, v54
	s_waitcnt lgkmcnt(0)
	v_cvt_pk_bf16_f32 v51, v6, v7
	ds_read2_b32 v[6:7], v41 offset0:24 offset1:57
	v_lshl_add_u64 v[56:57], v[52:53], 0, v[56:57]
	v_ashrrev_i32_e32 v55, 31, v54
	global_store_dwordx4 v[56:57], v[48:51], off
	v_lshlrev_b64 v[54:55], 13, v[54:55]
	v_lshl_add_u64 v[52:53], v[52:53], 0, v[54:55]
	s_waitcnt lgkmcnt(0)
	v_cvt_pk_bf16_f32 v48, v6, v7
	ds_read2_b32 v[6:7], v41 offset0:90 offset1:123
	s_waitcnt lgkmcnt(0)
	v_cvt_pk_bf16_f32 v49, v6, v7
	ds_read2_b32 v[6:7], v41 offset0:156 offset1:189
	s_waitcnt lgkmcnt(0)
	v_cvt_pk_bf16_f32 v50, v6, v7
	ds_read2_b32 v[6:7], v41 offset0:222 offset1:255
	s_waitcnt lgkmcnt(0)
	v_cvt_pk_bf16_f32 v51, v6, v7
	global_store_dwordx4 v[52:53], v[48:51], off
	s_waitcnt lgkmcnt(0)
	s_add_i32 s0, s8, 0x200
	v_add_u32_e32 v40, 0x4000, v40
	v_add_u32_e32 v1, 0x4000, v1
	s_cmpk_lt_i32 s8, 0x1e00
	s_mov_b32 s8, s0
	s_cbranch_scc0 .LBB0_1408
.LBB0_1376:
	s_ashr_i32 s0, s8, 31
	s_lshr_b32 s0, s0, 25
	s_add_i32 s0, s8, s0
	s_ashr_i32 s1, s0, 7
	s_lshl_b32 s0, s1, 6
	s_lshl_b32 s1, s1, 12
	s_sub_i32 s10, s9, s1
	v_add_u32_e32 v2, s10, v1
	s_lshl_b32 s4, s0, 14
	v_lshlrev_b32_e32 v60, 2, v2
	s_add_u32 s6, s82, s4
	v_lshl_add_u32 v60, v8, 14, v60
	s_addc_u32 s7, s83, 0
	v_mov_b32_e32 v62, v42
	global_load_dword v64, v60, s[6:7] nt
	v_add_u32_e32 v60, 0x8000, v60
	global_load_dword v65, v60, s[6:7] nt
	v_add_u32_e32 v60, 0x8000, v60
	global_load_dword v66, v60, s[6:7] nt
	v_add_u32_e32 v60, 0x8000, v60
	global_load_dword v67, v60, s[6:7] nt
	v_add_u32_e32 v60, 0x8000, v60
	global_load_dword v68, v60, s[6:7] nt
	v_add_u32_e32 v60, 0x8000, v60
	global_load_dword v69, v60, s[6:7] nt
	v_add_u32_e32 v60, 0x8000, v60
	global_load_dword v70, v60, s[6:7] nt
	v_add_u32_e32 v60, 0x8000, v60
	global_load_dword v71, v60, s[6:7] nt
	v_add_u32_e32 v60, 0x8000, v60
	global_load_dword v72, v60, s[6:7] nt
	v_add_u32_e32 v60, 0x8000, v60
	global_load_dword v73, v60, s[6:7] nt
	v_add_u32_e32 v60, 0x8000, v60
	global_load_dword v74, v60, s[6:7] nt
	v_add_u32_e32 v60, 0x8000, v60
	global_load_dword v75, v60, s[6:7] nt
	v_add_u32_e32 v60, 0x8000, v60
	global_load_dword v76, v60, s[6:7] nt
	v_add_u32_e32 v60, 0x8000, v60
	global_load_dword v77, v60, s[6:7] nt
	v_add_u32_e32 v60, 0x8000, v60
	global_load_dword v78, v60, s[6:7] nt
	v_add_u32_e32 v60, 0x8000, v60
	global_load_dword v79, v60, s[6:7] nt
	v_add_u32_e32 v60, 0x8000, v60
	global_load_dword v80, v60, s[6:7] nt
	v_add_u32_e32 v60, 0x8000, v60
	global_load_dword v81, v60, s[6:7] nt
	v_add_u32_e32 v60, 0x8000, v60
	global_load_dword v82, v60, s[6:7] nt
	v_add_u32_e32 v60, 0x8000, v60
	global_load_dword v83, v60, s[6:7] nt
	v_add_u32_e32 v60, 0x8000, v60
	global_load_dword v84, v60, s[6:7] nt
	v_add_u32_e32 v60, 0x8000, v60
	global_load_dword v85, v60, s[6:7] nt
	v_add_u32_e32 v60, 0x8000, v60
	global_load_dword v86, v60, s[6:7] nt
	v_add_u32_e32 v60, 0x8000, v60
	global_load_dword v87, v60, s[6:7] nt
	v_add_u32_e32 v60, 0x8000, v60
	global_load_dword v88, v60, s[6:7] nt
	v_add_u32_e32 v60, 0x8000, v60
	global_load_dword v89, v60, s[6:7] nt
	v_add_u32_e32 v60, 0x8000, v60
	global_load_dword v90, v60, s[6:7] nt
	v_add_u32_e32 v60, 0x8000, v60
	global_load_dword v91, v60, s[6:7] nt
	v_add_u32_e32 v60, 0x8000, v60
	global_load_dword v92, v60, s[6:7] nt
	v_add_u32_e32 v60, 0x8000, v60
	global_load_dword v93, v60, s[6:7] nt
	v_add_u32_e32 v60, 0x8000, v60
	global_load_dword v94, v60, s[6:7] nt
	v_add_u32_e32 v60, 0x8000, v60
	global_load_dword v95, v60, s[6:7] nt
	s_waitcnt vmcnt(30)
	ds_write2_b32 v62, v64, v65 offset1:66
	s_waitcnt vmcnt(28)
	ds_write2_b32 v62, v66, v67 offset0:132 offset1:198
	v_add_u32_e32 v62, 0x420, v62
	s_waitcnt vmcnt(26)
	ds_write2_b32 v62, v68, v69 offset1:66
	s_waitcnt vmcnt(24)
	ds_write2_b32 v62, v70, v71 offset0:132 offset1:198
	v_add_u32_e32 v62, 0x420, v62
	s_waitcnt vmcnt(22)
	ds_write2_b32 v62, v72, v73 offset1:66
	s_waitcnt vmcnt(20)
	ds_write2_b32 v62, v74, v75 offset0:132 offset1:198
	v_add_u32_e32 v62, 0x420, v62
	s_waitcnt vmcnt(18)
	ds_write2_b32 v62, v76, v77 offset1:66
	s_waitcnt vmcnt(16)
	ds_write2_b32 v62, v78, v79 offset0:132 offset1:198
	v_add_u32_e32 v62, 0x420, v62
	s_waitcnt lgkmcnt(0)
	s_waitcnt vmcnt(14)
	ds_write2_b32 v62, v80, v81 offset1:66
	s_waitcnt vmcnt(12)
	ds_write2_b32 v62, v82, v83 offset0:132 offset1:198
	v_add_u32_e32 v62, 0x420, v62
	s_waitcnt vmcnt(10)
	ds_write2_b32 v62, v84, v85 offset1:66
	s_waitcnt vmcnt(8)
	ds_write2_b32 v62, v86, v87 offset0:132 offset1:198
	v_add_u32_e32 v62, 0x420, v62
	s_waitcnt vmcnt(6)
	ds_write2_b32 v62, v88, v89 offset1:66
	s_waitcnt vmcnt(4)
	ds_write2_b32 v62, v90, v91 offset0:132 offset1:198
	v_add_u32_e32 v62, 0x420, v62
	s_waitcnt vmcnt(2)
	ds_write2_b32 v62, v92, v93 offset1:66
	s_waitcnt vmcnt(0)
	ds_write2_b32 v62, v94, v95 offset0:132 offset1:198
	s_branch .Le14_rd
